# MLA loop: K chunk-1 fragment reads moved behind the first MFMA, V reads reordered behind K chunk 2; diff: ALiBi tile base updated incrementally
# speedup vs baseline: 1.0087x; 1.0087x over previous
; template <int DQK, int DV, int FLAGS, int qp, int kp, int vts, int op> ...
;     ...
;             if (FLAGS & AF_ALIBI) { const float ab = -slope2 * (float)nrel - ((FLAGS & AF_ROBUST) ? 0.f : m);
; #pragma unroll
;                 for (int r = 0; r < 16; ++r) { const float c = (float)(16 * (r >> 3) + (r & 7)); p0[r] = __builtin_fmaf(slope2, c, ab); p1[r] = __builtin_fmaf(slope2, c + 32.f, ab); }
;             } else if (FLAGS & AF_ROBUST) {
; #pragma unroll
;                 for (int r = 0; r < 16; ++r) { p0[r] = 0.f; p1[r] = 0.f; }
;             } else { p0 = negm; p1 = negm; }
;             __builtin_amdgcn_sched_barrier(0);
; #pragma unroll
;             for (int c = 0; c < ND0 / 2; ++c) {
;                 if (c + 1 < ND0 / 2) {
; #pragma unroll
;                     for (int i = 0; i < 2; ++i) { kf[(c + 1) & 1][2 * i] = *(const LAS bf16x8*)(kb + (2 * c + 2 + i) * 32); kf[(c + 1) & 1][2 * i + 1] = *(const LAS bf16x8*)(kb + 32 * KROW + (2 * c + 2 + i) * 32); }
;                 }
; #pragma unroll
;                 for (int i = 0; i < 2; ++i) {
;                     p0 = __builtin_amdgcn_mfma_f32_32x32x16_bf16(kf[c & 1][2 * i], qr[2 * c + i], p0, 0, 0, 0);
;                     p1 = __builtin_amdgcn_mfma_f32_32x32x16_bf16(kf[c & 1][2 * i + 1], qr[2 * c + i], p1, 0, 0, 0);
;                 }
;                 __builtin_amdgcn_sched_barrier(0);
;             }
;             if (more) ATT_GLOAD((FLAGS & AF_REV) ? t - 1 : t + 1);
;     ...
;             for (int r = 0; r < 16; ++r) { p0[r] = __builtin_amdgcn_exp2f(p0[r]); p1[r] = __builtin_amdgcn_exp2f(p1[r]); }
; #pragma unroll
;             for (int r = 0; r < 16; r += 2) { rs2 += (f32x2){p0[r], p0[r + 1]}; rs2 += (f32x2){p1[r], p1[r + 1]}; }
;             l += rs2.x + rs2.y;
;             bf16x8 pf[4];
;             pf[0] = pack_bf16x8(p0, 0); pf[1] = pack_bf16x8(p0, 8); pf[2] = pack_bf16x8(p1, 0); pf[3] = pack_bf16x8(p1, 8);
;             __builtin_amdgcn_sched_barrier(0);
; #pragma unroll
;             for (int d = 0; d < NDB; ++d) {
;                 if (d + 1 < NDB) {
; #pragma unroll
;                     for (int ks = 0; ks < 4; ++ks) vf[(d + 1) & 1][ks] = *(const LAS bf16x8*)(vb + (d + 1) * 32 * VROW + ks * 32);
;                 }
; #pragma unroll
;                 for (int ks = 0; ks < 4; ++ks) o[d] = __builtin_amdgcn_mfma_f32_32x32x16_bf16(vf[d & 1][ks], pf[ks], o[d], 0, 0, 0);
.Ld_noqk0:
.Ld_top0:
	s_cmp_le_i32 s23, s24
	s_cbranch_scc1 .Ld_gen0
	s_add_i32 s13, s23, 1
	s_cmp_ge_i32 s13, s3
	s_cbranch_scc1 .Ld_gen0
	ds_read_b128 v[224:227], v250 offset:41472
	ds_read_b128 v[228:231], v250 offset:41504
	ds_read_b128 v[232:235], v250 offset:41536
	ds_read_b128 v[236:239], v250 offset:41568
	v_mfma_f32_32x32x16_bf16 v[64:79], v[160:163], v[112:115], v[64:79]
	v_exp_f32_e32 v80, v80
	v_exp_f32_e32 v81, v81
	v_exp_f32_e32 v96, v96
	v_exp_f32_e32 v97, v97
	v_fmamk_f32 v242, v14, 0xc2800000, v242
	v_mfma_f32_32x32x16_bf16 v[64:79], v[164:167], v[116:119], v[64:79]
	v_add_f32_e32 v240, v80, v199
	v_exp_f32_e32 v82, v82
	v_exp_f32_e32 v83, v83
	v_add_f32_e32 v240, v96, v240
	v_fma_f32 v128, v14, s8, v242
	v_mfma_f32_32x32x16_bf16 v[64:79], v[168:171], v[120:123], v[64:79]
	v_add_f32_e32 v241, v81, v97
	v_exp_f32_e32 v98, v98
	v_exp_f32_e32 v99, v99
	v_add_f32_e32 v240, v82, v240
	v_fma_f32 v129, v14, s9, v242
	v_mfma_f32_32x32x16_bf16 v[64:79], v[172:175], v[124:127], v[64:79]
	v_add_f32_e32 v241, v83, v241
	v_exp_f32_e32 v84, v84
	v_exp_f32_e32 v85, v85
	v_add_f32_e32 v240, v98, v240
	v_fma_f32 v130, v14, s96, v242
	ds_read_b128 v[160:163], v250 offset:46080
	ds_read_b128 v[164:167], v250 offset:46112
	ds_read_b128 v[168:171], v250 offset:46144
	ds_read_b128 v[172:175], v250 offset:46176
	s_waitcnt lgkmcnt(4)
	v_mfma_f32_32x32x16_bf16 v[48:63], v[224:227], v[112:115], v[48:63]
	v_add_f32_e32 v241, v99, v241
	v_exp_f32_e32 v100, v100
	v_exp_f32_e32 v101, v101
	v_add_f32_e32 v240, v84, v240
	v_fma_f32 v131, v14, s97, v242
	s_waitcnt vmcnt(0)
	ds_write_b128 v248, v[148:151] offset:0
	v_mfma_f32_32x32x16_bf16 v[48:63], v[228:231], v[116:119], v[48:63]
	v_add_f32_e32 v241, v85, v241
	v_exp_f32_e32 v86, v86
	v_exp_f32_e32 v87, v87
	v_add_f32_e32 v240, v100, v240
	v_fma_f32 v132, v14, s94, v242
	ds_write_b128 v249, v[152:155] offset:9216
	v_mfma_f32_32x32x16_bf16 v[48:63], v[232:235], v[120:123], v[48:63]
	v_add_f32_e32 v241, v101, v241
	v_exp_f32_e32 v102, v102
	v_exp_f32_e32 v103, v103
	v_add_f32_e32 v240, v86, v240
	v_fma_f32 v133, v14, s95, v242
	ds_write_b128 v249, v[156:159] offset:18432
	v_mfma_f32_32x32x16_bf16 v[48:63], v[236:239], v[124:127], v[48:63]
	v_add_f32_e32 v241, v87, v241
	v_exp_f32_e32 v88, v88
	v_exp_f32_e32 v89, v89
	v_add_f32_e32 v240, v102, v240
	v_fma_f32 v134, v14, s92, v242
	ds_read_b128 v[224:227], v250 offset:50688
	ds_read_b128 v[228:231], v250 offset:50720
	ds_read_b128 v[232:235], v250 offset:50752
	ds_read_b128 v[236:239], v250 offset:50784
	s_waitcnt lgkmcnt(4)
	v_mfma_f32_32x32x16_bf16 v[32:47], v[160:163], v[112:115], v[32:47]
	v_add_f32_e32 v241, v103, v241
	v_exp_f32_e32 v104, v104
	v_exp_f32_e32 v105, v105
	v_add_f32_e32 v240, v88, v240
	v_fma_f32 v135, v14, s93, v242
	v_mfma_f32_32x32x16_bf16 v[32:47], v[164:167], v[116:119], v[32:47]
	v_add_f32_e32 v241, v89, v241
	v_exp_f32_e32 v90, v90
	v_exp_f32_e32 v91, v91
	v_add_f32_e32 v240, v104, v240
	v_fma_f32 v136, v14, s90, v242
	s_ashr_i32 s35, s34, 31
	s_lshl_b64 s[6:7], s[34:35], 17
	s_lshl_b64 s[10:11], s[34:35], 7
	s_add_u32 s10, s18, s10
	s_addc_u32 s11, s19, s11
	s_add_u32 s6, s6, s100
	s_addc_u32 s7, s7, s101
	global_load_dwordx4 v[148:151], v243, s[6:7]
	v_mfma_f32_32x32x16_bf16 v[32:47], v[168:171], v[120:123], v[32:47]
	v_add_f32_e32 v241, v105, v241
	v_exp_f32_e32 v106, v106
	v_exp_f32_e32 v107, v107
	v_add_f32_e32 v240, v90, v240
	v_fma_f32 v137, v14, s91, v242
	global_load_dwordx4 v[152:155], v0, s[10:11]
	v_mfma_f32_32x32x16_bf16 v[32:47], v[172:175], v[124:127], v[32:47]
	v_add_f32_e32 v241, v91, v241
	v_exp_f32_e32 v92, v92
	v_exp_f32_e32 v93, v93
	v_add_f32_e32 v240, v106, v240
	v_fma_f32 v138, v14, s88, v242
	global_load_dwordx4 v[156:159], v196, s[10:11]
	s_add_i32 s34, s34, -1
	ds_read_b128 v[160:163], v244 offset:32256
	ds_read_b128 v[164:167], v244 offset:32288
	ds_read_b128 v[168:171], v244 offset:32320
	ds_read_b128 v[172:175], v244 offset:32352
	s_waitcnt lgkmcnt(4)
	v_mfma_f32_32x32x16_bf16 v[16:31], v[224:227], v[112:115], v[16:31]
	v_add_f32_e32 v241, v107, v241
	v_exp_f32_e32 v108, v108
	v_exp_f32_e32 v109, v109
	v_add_f32_e32 v240, v92, v240
	v_fma_f32 v139, v14, s89, v242
	v_mfma_f32_32x32x16_bf16 v[16:31], v[228:231], v[116:119], v[16:31]
	v_add_f32_e32 v241, v93, v241
	v_exp_f32_e32 v94, v94
	v_exp_f32_e32 v95, v95
	v_add_f32_e32 v240, v108, v240
	v_fma_f32 v140, v14, s86, v242
	v_mfma_f32_32x32x16_bf16 v[16:31], v[232:235], v[120:123], v[16:31]
	v_add_f32_e32 v241, v109, v241
	v_exp_f32_e32 v110, v110
	v_exp_f32_e32 v111, v111
	v_add_f32_e32 v240, v94, v240
	v_fma_f32 v141, v14, s87, v242
	v_mfma_f32_32x32x16_bf16 v[16:31], v[236:239], v[124:127], v[16:31]
	v_add_f32_e32 v241, v95, v241
	v_fma_f32 v142, v14, s78, v242
	v_fma_f32 v143, v14, s79, v242
	ds_read_b128 v[224:227], v244 offset:27648
	ds_read_b128 v[228:231], v244 offset:27680
	ds_read_b128 v[232:235], v244 offset:27712
	ds_read_b128 v[236:239], v244 offset:27744
	s_waitcnt lgkmcnt(4)
	v_mfma_f32_32x32x16_bf16 v[128:143], v[160:163], v[2:5], v[128:143]
	v_mov_b32_e32 v112, v242
	v_add_f32_e32 v113, v14, v242
	v_fma_f32 v114, v14, s62, v242
	v_fma_f32 v115, v14, s63, v242
	v_mfma_f32_32x32x16_bf16 v[128:143], v[164:167], v[6:9], v[128:143]
	v_fma_f32 v116, v14, s64, v242
	v_fma_f32 v117, v14, s65, v242
	v_fma_f32 v118, v14, s66, v242
	v_fma_f32 v119, v14, s67, v242
	v_mfma_f32_32x32x16_bf16 v[128:143], v[168:171], v[10:13], v[128:143]
	v_fma_f32 v120, v14, s68, v242
	v_fma_f32 v121, v14, s69, v242
	v_fma_f32 v122, v14, s70, v242
	v_fma_f32 v123, v14, s71, v242
	v_mfma_f32_32x32x16_bf16 v[128:143], v[172:175], v[144:147], v[128:143]
	v_fma_f32 v124, v14, s72, v242
	v_fma_f32 v125, v14, s73, v242
	v_fma_f32 v126, v14, s76, v242
	v_fma_f32 v127, v14, s77, v242
	ds_read_b128 v[160:163], v251 offset:9216
	ds_read_b128 v[164:167], v251 offset:9248
	ds_read_b128 v[168:171], v251 offset:9280
	ds_read_b128 v[172:175], v251 offset:9312
	s_waitcnt lgkmcnt(4)
	v_mfma_f32_32x32x16_bf16 v[112:127], v[224:227], v[2:5], v[112:127]
	s_nop 0
	v_add_f32_e32 v240, v110, v240
	v_add_f32_e32 v241, v111, v241
	v_cvt_pk_bf16_f32 v80, v80, v81
	v_cvt_pk_bf16_f32 v81, v82, v83
	v_cvt_pk_bf16_f32 v82, v84, v85
	v_mfma_f32_32x32x16_bf16 v[112:127], v[228:231], v[6:9], v[112:127]
	v_cvt_pk_bf16_f32 v83, v86, v87
	v_cvt_pk_bf16_f32 v84, v88, v89
	v_cvt_pk_bf16_f32 v85, v90, v91
	v_cvt_pk_bf16_f32 v86, v92, v93
	v_cvt_pk_bf16_f32 v87, v94, v95
	v_cvt_pk_bf16_f32 v88, v96, v97
	v_mfma_f32_32x32x16_bf16 v[112:127], v[232:235], v[10:13], v[112:127]
	v_cvt_pk_bf16_f32 v89, v98, v99
	v_cvt_pk_bf16_f32 v90, v100, v101
	v_cvt_pk_bf16_f32 v91, v102, v103
	v_cvt_pk_bf16_f32 v92, v104, v105
	v_cvt_pk_bf16_f32 v93, v106, v107
	v_cvt_pk_bf16_f32 v94, v108, v109
	v_mfma_f32_32x32x16_bf16 v[112:127], v[236:239], v[144:147], v[112:127]
	v_cvt_pk_bf16_f32 v95, v110, v111
	v_add_f32_e32 v199, v240, v241
	s_branch .Ld_tail0

; template <int DQK, int DV, int FLAGS, int qp, int kp, int vts, int op> ...
;     ...
;             if (FLAGS & AF_ALIBI) { const float ab = -slope2 * (float)nrel - ((FLAGS & AF_ROBUST) ? 0.f : m);
; #pragma unroll
;                 for (int r = 0; r < 16; ++r) { const float c = (float)(16 * (r >> 3) + (r & 7)); p0[r] = __builtin_fmaf(slope2, c, ab); p1[r] = __builtin_fmaf(slope2, c + 32.f, ab); }
;             } else if (FLAGS & AF_ROBUST) {
; #pragma unroll
;                 for (int r = 0; r < 16; ++r) { p0[r] = 0.f; p1[r] = 0.f; }
;             } else { p0 = negm; p1 = negm; }
;             __builtin_amdgcn_sched_barrier(0);
; #pragma unroll
;             for (int c = 0; c < ND0 / 2; ++c) {
;                 if (c + 1 < ND0 / 2) {
; #pragma unroll
;                     for (int i = 0; i < 2; ++i) { kf[(c + 1) & 1][2 * i] = *(const LAS bf16x8*)(kb + (2 * c + 2 + i) * 32); kf[(c + 1) & 1][2 * i + 1] = *(const LAS bf16x8*)(kb + 32 * KROW + (2 * c + 2 + i) * 32); }
;                 }
; #pragma unroll
;                 for (int i = 0; i < 2; ++i) {
;                     p0 = __builtin_amdgcn_mfma_f32_32x32x16_bf16(kf[c & 1][2 * i], qr[2 * c + i], p0, 0, 0, 0);
;                     p1 = __builtin_amdgcn_mfma_f32_32x32x16_bf16(kf[c & 1][2 * i + 1], qr[2 * c + i], p1, 0, 0, 0);
;                 }
;                 __builtin_amdgcn_sched_barrier(0);
;             }
;             if (more) ATT_GLOAD((FLAGS & AF_REV) ? t - 1 : t + 1);
;     ...
;             for (int r = 0; r < 16; ++r) { p0[r] = __builtin_amdgcn_exp2f(p0[r]); p1[r] = __builtin_amdgcn_exp2f(p1[r]); }
; #pragma unroll
;             for (int r = 0; r < 16; r += 2) { rs2 += (f32x2){p0[r], p0[r + 1]}; rs2 += (f32x2){p1[r], p1[r + 1]}; }
;             l += rs2.x + rs2.y;
;             bf16x8 pf[4];
;             pf[0] = pack_bf16x8(p0, 0); pf[1] = pack_bf16x8(p0, 8); pf[2] = pack_bf16x8(p1, 0); pf[3] = pack_bf16x8(p1, 8);
;             __builtin_amdgcn_sched_barrier(0);
; #pragma unroll
;             for (int d = 0; d < NDB; ++d) {
;                 if (d + 1 < NDB) {
; #pragma unroll
;                     for (int ks = 0; ks < 4; ++ks) vf[(d + 1) & 1][ks] = *(const LAS bf16x8*)(vb + (d + 1) * 32 * VROW + ks * 32);
;                 }
; #pragma unroll
;                 for (int ks = 0; ks < 4; ++ks) o[d] = __builtin_amdgcn_mfma_f32_32x32x16_bf16(vf[d & 1][ks], pf[ks], o[d], 0, 0, 0);
.Ld_top1:
	s_cmp_le_i32 s23, s24
	s_cbranch_scc1 .Ld_gen1
	s_add_i32 s13, s23, 1
	s_cmp_ge_i32 s13, s3
	s_cbranch_scc1 .Ld_gen1
	ds_read_b128 v[224:227], v251 offset:13824
	ds_read_b128 v[228:231], v251 offset:13856
	ds_read_b128 v[232:235], v251 offset:13888
	ds_read_b128 v[236:239], v251 offset:13920
	v_mfma_f32_32x32x16_bf16 v[64:79], v[160:163], v[80:83], v[64:79]
	v_exp_f32_e32 v112, v112
	v_exp_f32_e32 v113, v113
	v_exp_f32_e32 v128, v128
	v_exp_f32_e32 v129, v129
	v_fmamk_f32 v242, v14, 0xc2800000, v242
	v_mfma_f32_32x32x16_bf16 v[64:79], v[164:167], v[84:87], v[64:79]
	v_add_f32_e32 v240, v112, v199
	v_exp_f32_e32 v114, v114
	v_exp_f32_e32 v115, v115
	v_add_f32_e32 v240, v128, v240
	v_fma_f32 v96, v14, s8, v242
	v_mfma_f32_32x32x16_bf16 v[64:79], v[168:171], v[88:91], v[64:79]
	v_add_f32_e32 v241, v113, v129
	v_exp_f32_e32 v130, v130
	v_exp_f32_e32 v131, v131
	v_add_f32_e32 v240, v114, v240
	v_fma_f32 v97, v14, s9, v242
	v_mfma_f32_32x32x16_bf16 v[64:79], v[172:175], v[92:95], v[64:79]
	v_add_f32_e32 v241, v115, v241
	v_exp_f32_e32 v116, v116
	v_exp_f32_e32 v117, v117
	v_add_f32_e32 v240, v130, v240
	v_fma_f32 v98, v14, s96, v242
	ds_read_b128 v[160:163], v251 offset:18432
	ds_read_b128 v[164:167], v251 offset:18464
	ds_read_b128 v[168:171], v251 offset:18496
	ds_read_b128 v[172:175], v251 offset:18528
	s_waitcnt lgkmcnt(4)
	v_mfma_f32_32x32x16_bf16 v[48:63], v[224:227], v[80:83], v[48:63]
	v_add_f32_e32 v241, v131, v241
	v_exp_f32_e32 v132, v132
	v_exp_f32_e32 v133, v133
	v_add_f32_e32 v240, v116, v240
	v_fma_f32 v99, v14, s97, v242
	s_waitcnt vmcnt(0)
	ds_write_b128 v248, v[148:151] offset:27648
	v_mfma_f32_32x32x16_bf16 v[48:63], v[228:231], v[84:87], v[48:63]
	v_add_f32_e32 v241, v117, v241
	v_exp_f32_e32 v118, v118
	v_exp_f32_e32 v119, v119
	v_add_f32_e32 v240, v132, v240
	v_fma_f32 v100, v14, s94, v242
	ds_write_b128 v249, v[152:155] offset:36864
	v_mfma_f32_32x32x16_bf16 v[48:63], v[232:235], v[88:91], v[48:63]
	v_add_f32_e32 v241, v133, v241
	v_exp_f32_e32 v134, v134
	v_exp_f32_e32 v135, v135
	v_add_f32_e32 v240, v118, v240
	v_fma_f32 v101, v14, s95, v242
	ds_write_b128 v249, v[156:159] offset:46080
	v_mfma_f32_32x32x16_bf16 v[48:63], v[236:239], v[92:95], v[48:63]
	v_add_f32_e32 v241, v119, v241
	v_exp_f32_e32 v120, v120
	v_exp_f32_e32 v121, v121
	v_add_f32_e32 v240, v134, v240
	v_fma_f32 v102, v14, s92, v242
	ds_read_b128 v[224:227], v251 offset:23040
	ds_read_b128 v[228:231], v251 offset:23072
	ds_read_b128 v[232:235], v251 offset:23104
	ds_read_b128 v[236:239], v251 offset:23136
	s_waitcnt lgkmcnt(4)
	v_mfma_f32_32x32x16_bf16 v[32:47], v[160:163], v[80:83], v[32:47]
	v_add_f32_e32 v241, v135, v241
	v_exp_f32_e32 v136, v136
	v_exp_f32_e32 v137, v137
	v_add_f32_e32 v240, v120, v240
	v_fma_f32 v103, v14, s93, v242
	v_mfma_f32_32x32x16_bf16 v[32:47], v[164:167], v[84:87], v[32:47]
	v_add_f32_e32 v241, v121, v241
	v_exp_f32_e32 v122, v122
	v_exp_f32_e32 v123, v123
	v_add_f32_e32 v240, v136, v240
	v_fma_f32 v104, v14, s90, v242
	s_ashr_i32 s35, s34, 31
	s_lshl_b64 s[6:7], s[34:35], 17
	s_lshl_b64 s[10:11], s[34:35], 7
	s_add_u32 s10, s18, s10
	s_addc_u32 s11, s19, s11
	s_add_u32 s6, s6, s100
	s_addc_u32 s7, s7, s101
	global_load_dwordx4 v[148:151], v243, s[6:7]
	v_mfma_f32_32x32x16_bf16 v[32:47], v[168:171], v[88:91], v[32:47]
	v_add_f32_e32 v241, v137, v241
	v_exp_f32_e32 v138, v138
	v_exp_f32_e32 v139, v139
	v_add_f32_e32 v240, v122, v240
	v_fma_f32 v105, v14, s91, v242
	global_load_dwordx4 v[152:155], v0, s[10:11]
	v_mfma_f32_32x32x16_bf16 v[32:47], v[172:175], v[92:95], v[32:47]
	v_add_f32_e32 v241, v123, v241
	v_exp_f32_e32 v124, v124
	v_exp_f32_e32 v125, v125
	v_add_f32_e32 v240, v138, v240
	v_fma_f32 v106, v14, s88, v242
	global_load_dwordx4 v[156:159], v196, s[10:11]
	s_add_i32 s34, s34, -1
	ds_read_b128 v[160:163], v245 offset:4608
	ds_read_b128 v[164:167], v245 offset:4640
	ds_read_b128 v[168:171], v245 offset:4672
	ds_read_b128 v[172:175], v245 offset:4704
	s_waitcnt lgkmcnt(4)
	v_mfma_f32_32x32x16_bf16 v[16:31], v[224:227], v[80:83], v[16:31]
	v_add_f32_e32 v241, v139, v241
	v_exp_f32_e32 v140, v140
	v_exp_f32_e32 v141, v141
	v_add_f32_e32 v240, v124, v240
	v_fma_f32 v107, v14, s89, v242
	v_mfma_f32_32x32x16_bf16 v[16:31], v[228:231], v[84:87], v[16:31]
	v_add_f32_e32 v241, v125, v241
	v_exp_f32_e32 v126, v126
	v_exp_f32_e32 v127, v127
	v_add_f32_e32 v240, v140, v240
	v_fma_f32 v108, v14, s86, v242
	v_mfma_f32_32x32x16_bf16 v[16:31], v[232:235], v[88:91], v[16:31]
	v_add_f32_e32 v241, v141, v241
	v_exp_f32_e32 v142, v142
	v_exp_f32_e32 v143, v143
	v_add_f32_e32 v240, v126, v240
	v_fma_f32 v109, v14, s87, v242
	v_mfma_f32_32x32x16_bf16 v[16:31], v[236:239], v[92:95], v[16:31]
	v_add_f32_e32 v241, v127, v241
	v_fma_f32 v110, v14, s78, v242
	v_fma_f32 v111, v14, s79, v242
	ds_read_b128 v[224:227], v245 offset:0
	ds_read_b128 v[228:231], v245 offset:32
	ds_read_b128 v[232:235], v245 offset:64
	ds_read_b128 v[236:239], v245 offset:96
	s_waitcnt lgkmcnt(4)
	v_mfma_f32_32x32x16_bf16 v[96:111], v[160:163], v[2:5], v[96:111]
	v_mov_b32_e32 v80, v242
	v_add_f32_e32 v81, v14, v242
	v_fma_f32 v82, v14, s62, v242
	v_fma_f32 v83, v14, s63, v242
	v_mfma_f32_32x32x16_bf16 v[96:111], v[164:167], v[6:9], v[96:111]
	v_fma_f32 v84, v14, s64, v242
	v_fma_f32 v85, v14, s65, v242
	v_fma_f32 v86, v14, s66, v242
	v_fma_f32 v87, v14, s67, v242
	v_mfma_f32_32x32x16_bf16 v[96:111], v[168:171], v[10:13], v[96:111]
	v_fma_f32 v88, v14, s68, v242
	v_fma_f32 v89, v14, s69, v242
	v_fma_f32 v90, v14, s70, v242
	v_fma_f32 v91, v14, s71, v242
	v_mfma_f32_32x32x16_bf16 v[96:111], v[172:175], v[144:147], v[96:111]
	v_fma_f32 v92, v14, s72, v242
	v_fma_f32 v93, v14, s73, v242
	v_fma_f32 v94, v14, s76, v242
	v_fma_f32 v95, v14, s77, v242
	ds_read_b128 v[160:163], v251 offset:36864
	ds_read_b128 v[164:167], v251 offset:36896
	ds_read_b128 v[168:171], v251 offset:36928
	ds_read_b128 v[172:175], v251 offset:36960
	s_waitcnt lgkmcnt(4)
	v_mfma_f32_32x32x16_bf16 v[80:95], v[224:227], v[2:5], v[80:95]
	s_nop 0
	v_add_f32_e32 v240, v142, v240
	v_add_f32_e32 v241, v143, v241
	v_cvt_pk_bf16_f32 v112, v112, v113
	v_cvt_pk_bf16_f32 v113, v114, v115
	v_cvt_pk_bf16_f32 v114, v116, v117
	v_mfma_f32_32x32x16_bf16 v[80:95], v[228:231], v[6:9], v[80:95]
	v_cvt_pk_bf16_f32 v115, v118, v119
	v_cvt_pk_bf16_f32 v116, v120, v121
	v_cvt_pk_bf16_f32 v117, v122, v123
	v_cvt_pk_bf16_f32 v118, v124, v125
	v_cvt_pk_bf16_f32 v119, v126, v127
	v_cvt_pk_bf16_f32 v120, v128, v129
	v_mfma_f32_32x32x16_bf16 v[80:95], v[232:235], v[10:13], v[80:95]
	v_cvt_pk_bf16_f32 v121, v130, v131
	v_cvt_pk_bf16_f32 v122, v132, v133
	v_cvt_pk_bf16_f32 v123, v134, v135
	v_cvt_pk_bf16_f32 v124, v136, v137
	v_cvt_pk_bf16_f32 v125, v138, v139
	v_cvt_pk_bf16_f32 v126, v140, v141
	v_mfma_f32_32x32x16_bf16 v[80:95], v[236:239], v[144:147], v[80:95]
	v_cvt_pk_bf16_f32 v127, v142, v143
	v_add_f32_e32 v199, v240, v241
	s_branch .Ld_tail1

; template <int DQK, int DV, int FLAGS, int qp, int kp, int vts, int op> ...
;     ...
;             if (FLAGS & AF_ALIBI) { const float ab = -slope2 * (float)nrel - ((FLAGS & AF_ROBUST) ? 0.f : m);
; #pragma unroll
;                 for (int r = 0; r < 16; ++r) { const float c = (float)(16 * (r >> 3) + (r & 7)); p0[r] = __builtin_fmaf(slope2, c, ab); p1[r] = __builtin_fmaf(slope2, c + 32.f, ab); }
;             } else if (FLAGS & AF_ROBUST) {
; #pragma unroll
;                 for (int r = 0; r < 16; ++r) { p0[r] = 0.f; p1[r] = 0.f; }
;             } else { p0 = negm; p1 = negm; }
;             __builtin_amdgcn_sched_barrier(0);
; #pragma unroll
;             for (int c = 0; c < ND0 / 2; ++c) {
;                 if (c + 1 < ND0 / 2) {
; #pragma unroll
;                     for (int i = 0; i < 2; ++i) { kf[(c + 1) & 1][2 * i] = *(const LAS bf16x8*)(kb + (2 * c + 2 + i) * 32); kf[(c + 1) & 1][2 * i + 1] = *(const LAS bf16x8*)(kb + 32 * KROW + (2 * c + 2 + i) * 32); }
;                 }
; #pragma unroll
;                 for (int i = 0; i < 2; ++i) {
;                     p0 = __builtin_amdgcn_mfma_f32_32x32x16_bf16(kf[c & 1][2 * i], qr[2 * c + i], p0, 0, 0, 0);
;                     p1 = __builtin_amdgcn_mfma_f32_32x32x16_bf16(kf[c & 1][2 * i + 1], qr[2 * c + i], p1, 0, 0, 0);
;                 }
;                 __builtin_amdgcn_sched_barrier(0);
;             }
;             if (more) ATT_GLOAD((FLAGS & AF_REV) ? t - 1 : t + 1);
;     ...
;             for (int r = 0; r < 16; ++r) { p0[r] = __builtin_amdgcn_exp2f(p0[r]); p1[r] = __builtin_amdgcn_exp2f(p1[r]); }
; #pragma unroll
;             for (int r = 0; r < 16; r += 2) { rs2 += (f32x2){p0[r], p0[r + 1]}; rs2 += (f32x2){p1[r], p1[r + 1]}; }
;             l += rs2.x + rs2.y;
;             bf16x8 pf[4];
;             pf[0] = pack_bf16x8(p0, 0); pf[1] = pack_bf16x8(p0, 8); pf[2] = pack_bf16x8(p1, 0); pf[3] = pack_bf16x8(p1, 8);
;             __builtin_amdgcn_sched_barrier(0);
; #pragma unroll
;             for (int d = 0; d < NDB; ++d) {
;                 if (d + 1 < NDB) {
; #pragma unroll
;                     for (int ks = 0; ks < 4; ++ks) vf[(d + 1) & 1][ks] = *(const LAS bf16x8*)(vb + (d + 1) * 32 * VROW + ks * 32);
;                 }
; #pragma unroll
;                 for (int ks = 0; ks < 4; ++ks) o[d] = __builtin_amdgcn_mfma_f32_32x32x16_bf16(vf[d & 1][ks], pf[ks], o[d], 0, 0, 0);
.Ld_top2:
	s_cmp_le_i32 s23, s24
	s_cbranch_scc1 .Ld_gen2
	s_add_i32 s13, s23, 1
	s_cmp_ge_i32 s13, s3
	s_cbranch_scc1 .Ld_gen2
	ds_read_b128 v[224:227], v251 offset:41472
	ds_read_b128 v[228:231], v251 offset:41504
	ds_read_b128 v[232:235], v251 offset:41536
	ds_read_b128 v[236:239], v251 offset:41568
	v_mfma_f32_32x32x16_bf16 v[64:79], v[160:163], v[112:115], v[64:79]
	v_exp_f32_e32 v80, v80
	v_exp_f32_e32 v81, v81
	v_exp_f32_e32 v96, v96
	v_exp_f32_e32 v97, v97
	v_fmamk_f32 v242, v14, 0xc2800000, v242
	v_mfma_f32_32x32x16_bf16 v[64:79], v[164:167], v[116:119], v[64:79]
	v_add_f32_e32 v240, v80, v199
	v_exp_f32_e32 v82, v82
	v_exp_f32_e32 v83, v83
	v_add_f32_e32 v240, v96, v240
	v_fma_f32 v128, v14, s8, v242
	v_mfma_f32_32x32x16_bf16 v[64:79], v[168:171], v[120:123], v[64:79]
	v_add_f32_e32 v241, v81, v97
	v_exp_f32_e32 v98, v98
	v_exp_f32_e32 v99, v99
	v_add_f32_e32 v240, v82, v240
	v_fma_f32 v129, v14, s9, v242
	v_mfma_f32_32x32x16_bf16 v[64:79], v[172:175], v[124:127], v[64:79]
	v_add_f32_e32 v241, v83, v241
	v_exp_f32_e32 v84, v84
	v_exp_f32_e32 v85, v85
	v_add_f32_e32 v240, v98, v240
	v_fma_f32 v130, v14, s96, v242
	ds_read_b128 v[160:163], v251 offset:46080
	ds_read_b128 v[164:167], v251 offset:46112
	ds_read_b128 v[168:171], v251 offset:46144
	ds_read_b128 v[172:175], v251 offset:46176
	s_waitcnt lgkmcnt(4)
	v_mfma_f32_32x32x16_bf16 v[48:63], v[224:227], v[112:115], v[48:63]
	v_add_f32_e32 v241, v99, v241
	v_exp_f32_e32 v100, v100
	v_exp_f32_e32 v101, v101
	v_add_f32_e32 v240, v84, v240
	v_fma_f32 v131, v14, s97, v242
	s_waitcnt vmcnt(0)
	ds_write_b128 v204, v[148:151] offset:0
	v_mfma_f32_32x32x16_bf16 v[48:63], v[228:231], v[116:119], v[48:63]
	v_add_f32_e32 v241, v85, v241
	v_exp_f32_e32 v86, v86
	v_exp_f32_e32 v87, v87
	v_add_f32_e32 v240, v100, v240
	v_fma_f32 v132, v14, s94, v242
	ds_write_b128 v200, v[152:155] offset:9216
	v_mfma_f32_32x32x16_bf16 v[48:63], v[232:235], v[120:123], v[48:63]
	v_add_f32_e32 v241, v101, v241
	v_exp_f32_e32 v102, v102
	v_exp_f32_e32 v103, v103
	v_add_f32_e32 v240, v86, v240
	v_fma_f32 v133, v14, s95, v242
	ds_write_b128 v200, v[156:159] offset:18432
	v_mfma_f32_32x32x16_bf16 v[48:63], v[236:239], v[124:127], v[48:63]
	v_add_f32_e32 v241, v87, v241
	v_exp_f32_e32 v88, v88
	v_exp_f32_e32 v89, v89
	v_add_f32_e32 v240, v102, v240
	v_fma_f32 v134, v14, s92, v242
	ds_read_b128 v[224:227], v251 offset:50688
	ds_read_b128 v[228:231], v251 offset:50720
	ds_read_b128 v[232:235], v251 offset:50752
	ds_read_b128 v[236:239], v251 offset:50784
	s_waitcnt lgkmcnt(4)
	v_mfma_f32_32x32x16_bf16 v[32:47], v[160:163], v[112:115], v[32:47]
	v_add_f32_e32 v241, v103, v241
	v_exp_f32_e32 v104, v104
	v_exp_f32_e32 v105, v105
	v_add_f32_e32 v240, v88, v240
	v_fma_f32 v135, v14, s93, v242
	v_mfma_f32_32x32x16_bf16 v[32:47], v[164:167], v[116:119], v[32:47]
	v_add_f32_e32 v241, v89, v241
	v_exp_f32_e32 v90, v90
	v_exp_f32_e32 v91, v91
	v_add_f32_e32 v240, v104, v240
	v_fma_f32 v136, v14, s90, v242
	s_ashr_i32 s35, s34, 31
	s_lshl_b64 s[6:7], s[34:35], 17
	s_lshl_b64 s[10:11], s[34:35], 7
	s_add_u32 s10, s18, s10
	s_addc_u32 s11, s19, s11
	s_add_u32 s6, s6, s100
	s_addc_u32 s7, s7, s101
	global_load_dwordx4 v[148:151], v243, s[6:7]
	v_mfma_f32_32x32x16_bf16 v[32:47], v[168:171], v[120:123], v[32:47]
	v_add_f32_e32 v241, v105, v241
	v_exp_f32_e32 v106, v106
	v_exp_f32_e32 v107, v107
	v_add_f32_e32 v240, v90, v240
	v_fma_f32 v137, v14, s91, v242
	global_load_dwordx4 v[152:155], v0, s[10:11]
	v_mfma_f32_32x32x16_bf16 v[32:47], v[172:175], v[124:127], v[32:47]
	v_add_f32_e32 v241, v91, v241
	v_exp_f32_e32 v92, v92
	v_exp_f32_e32 v93, v93
	v_add_f32_e32 v240, v106, v240
	v_fma_f32 v138, v14, s88, v242
	global_load_dwordx4 v[156:159], v196, s[10:11]
	s_add_i32 s34, s34, -1
	ds_read_b128 v[160:163], v245 offset:32256
	ds_read_b128 v[164:167], v245 offset:32288
	ds_read_b128 v[168:171], v245 offset:32320
	ds_read_b128 v[172:175], v245 offset:32352
	s_waitcnt lgkmcnt(4)
	v_mfma_f32_32x32x16_bf16 v[16:31], v[224:227], v[112:115], v[16:31]
	v_add_f32_e32 v241, v107, v241
	v_exp_f32_e32 v108, v108
	v_exp_f32_e32 v109, v109
	v_add_f32_e32 v240, v92, v240
	v_fma_f32 v139, v14, s89, v242
	v_mfma_f32_32x32x16_bf16 v[16:31], v[228:231], v[116:119], v[16:31]
	v_add_f32_e32 v241, v93, v241
	v_exp_f32_e32 v94, v94
	v_exp_f32_e32 v95, v95
	v_add_f32_e32 v240, v108, v240
	v_fma_f32 v140, v14, s86, v242
	v_mfma_f32_32x32x16_bf16 v[16:31], v[232:235], v[120:123], v[16:31]
	v_add_f32_e32 v241, v109, v241
	v_exp_f32_e32 v110, v110
	v_exp_f32_e32 v111, v111
	v_add_f32_e32 v240, v94, v240
	v_fma_f32 v141, v14, s87, v242
	v_mfma_f32_32x32x16_bf16 v[16:31], v[236:239], v[124:127], v[16:31]
	v_add_f32_e32 v241, v95, v241
	v_fma_f32 v142, v14, s78, v242
	v_fma_f32 v143, v14, s79, v242
	ds_read_b128 v[224:227], v245 offset:27648
	ds_read_b128 v[228:231], v245 offset:27680
	ds_read_b128 v[232:235], v245 offset:27712
	ds_read_b128 v[236:239], v245 offset:27744
	s_waitcnt lgkmcnt(4)
	v_mfma_f32_32x32x16_bf16 v[128:143], v[160:163], v[2:5], v[128:143]
	v_mov_b32_e32 v112, v242
	v_add_f32_e32 v113, v14, v242
	v_fma_f32 v114, v14, s62, v242
	v_fma_f32 v115, v14, s63, v242
	v_mfma_f32_32x32x16_bf16 v[128:143], v[164:167], v[6:9], v[128:143]
	v_fma_f32 v116, v14, s64, v242
	v_fma_f32 v117, v14, s65, v242
	v_fma_f32 v118, v14, s66, v242
	v_fma_f32 v119, v14, s67, v242
	v_mfma_f32_32x32x16_bf16 v[128:143], v[168:171], v[10:13], v[128:143]
	v_fma_f32 v120, v14, s68, v242
	v_fma_f32 v121, v14, s69, v242
	v_fma_f32 v122, v14, s70, v242
	v_fma_f32 v123, v14, s71, v242
	v_mfma_f32_32x32x16_bf16 v[128:143], v[172:175], v[144:147], v[128:143]
	v_fma_f32 v124, v14, s72, v242
	v_fma_f32 v125, v14, s73, v242
	v_fma_f32 v126, v14, s76, v242
	v_fma_f32 v127, v14, s77, v242
	ds_read_b128 v[160:163], v250 offset:9216
	ds_read_b128 v[164:167], v250 offset:9248
	ds_read_b128 v[168:171], v250 offset:9280
	ds_read_b128 v[172:175], v250 offset:9312
	s_waitcnt lgkmcnt(4)
	v_mfma_f32_32x32x16_bf16 v[112:127], v[224:227], v[2:5], v[112:127]
	s_nop 0
	v_add_f32_e32 v240, v110, v240
	v_add_f32_e32 v241, v111, v241
	v_cvt_pk_bf16_f32 v80, v80, v81
	v_cvt_pk_bf16_f32 v81, v82, v83
	v_cvt_pk_bf16_f32 v82, v84, v85
	v_mfma_f32_32x32x16_bf16 v[112:127], v[228:231], v[6:9], v[112:127]
	v_cvt_pk_bf16_f32 v83, v86, v87
	v_cvt_pk_bf16_f32 v84, v88, v89
	v_cvt_pk_bf16_f32 v85, v90, v91
	v_cvt_pk_bf16_f32 v86, v92, v93
	v_cvt_pk_bf16_f32 v87, v94, v95
	v_cvt_pk_bf16_f32 v88, v96, v97
	v_mfma_f32_32x32x16_bf16 v[112:127], v[232:235], v[10:13], v[112:127]
	v_cvt_pk_bf16_f32 v89, v98, v99
	v_cvt_pk_bf16_f32 v90, v100, v101
	v_cvt_pk_bf16_f32 v91, v102, v103
	v_cvt_pk_bf16_f32 v92, v104, v105
	v_cvt_pk_bf16_f32 v93, v106, v107
	v_cvt_pk_bf16_f32 v94, v108, v109
	v_mfma_f32_32x32x16_bf16 v[112:127], v[236:239], v[144:147], v[112:127]
	v_cvt_pk_bf16_f32 v95, v110, v111
	v_add_f32_e32 v199, v240, v241
	s_branch .Ld_tail2

; #define LAS __attribute__((address_space(3)))
; template <int DQK, int DV, int FLAGS, int qp, int kp, int vts, int op> ...
;     ...
;             if (FLAGS & AF_ALIBI) { const float ab = -slope2 * (float)nrel - ((FLAGS & AF_ROBUST) ? 0.f : m);
; #pragma unroll
;                 for (int r = 0; r < 16; ++r) { const float c = (float)(16 * (r >> 3) + (r & 7)); p0[r] = __builtin_fmaf(slope2, c, ab); p1[r] = __builtin_fmaf(slope2, c + 32.f, ab); }
;     ...
;             f32x2 rs2 = {0.f, 0.f};
; #pragma unroll
;             for (int r = 0; r < 16; ++r) { p0[r] = __builtin_amdgcn_exp2f(p0[r]); p1[r] = __builtin_amdgcn_exp2f(p1[r]); }
; #pragma unroll
;             for (int r = 0; r < 16; r += 2) { rs2 += (f32x2){p0[r], p0[r + 1]}; rs2 += (f32x2){p1[r], p1[r + 1]}; }
;             l += rs2.x + rs2.y;
;             bf16x8 pf[4];
;             pf[0] = pack_bf16x8(p0, 0); pf[1] = pack_bf16x8(p0, 8); pf[2] = pack_bf16x8(p1, 0); pf[3] = pack_bf16x8(p1, 8);
;             __builtin_amdgcn_sched_barrier(0);
; #pragma unroll
;             for (int d = 0; d < NDB; ++d) {
;                 if (d + 1 < NDB) {
; #pragma unroll
;                     for (int ks = 0; ks < 4; ++ks) vf[(d + 1) & 1][ks] = *(const LAS bf16x8*)(vb + (d + 1) * 32 * VROW + ks * 32);
;                 }
; #pragma unroll
;                 for (int ks = 0; ks < 4; ++ks) o[d] = __builtin_amdgcn_mfma_f32_32x32x16_bf16(vf[d & 1][ks], pf[ks], o[d], 0, 0, 0);
.Ld_top3:
	s_cmp_le_i32 s23, s24
	s_cbranch_scc1 .Ld_gen3
	s_add_i32 s13, s23, 1
	s_cmp_ge_i32 s13, s3
	s_cbranch_scc1 .Ld_gen3
	ds_read_b128 v[224:227], v250 offset:13824
	ds_read_b128 v[228:231], v250 offset:13856
	ds_read_b128 v[232:235], v250 offset:13888
	ds_read_b128 v[236:239], v250 offset:13920
	v_mfma_f32_32x32x16_bf16 v[64:79], v[160:163], v[80:83], v[64:79]
	v_exp_f32_e32 v112, v112
	v_exp_f32_e32 v113, v113
	v_exp_f32_e32 v128, v128
	v_exp_f32_e32 v129, v129
	v_fmamk_f32 v242, v14, 0xc2800000, v242
	v_mfma_f32_32x32x16_bf16 v[64:79], v[164:167], v[84:87], v[64:79]
	v_add_f32_e32 v240, v112, v199
	v_exp_f32_e32 v114, v114
	v_exp_f32_e32 v115, v115
	v_add_f32_e32 v240, v128, v240
	v_fma_f32 v96, v14, s8, v242
	v_mfma_f32_32x32x16_bf16 v[64:79], v[168:171], v[88:91], v[64:79]
	v_add_f32_e32 v241, v113, v129
	v_exp_f32_e32 v130, v130
	v_exp_f32_e32 v131, v131
	v_add_f32_e32 v240, v114, v240
	v_fma_f32 v97, v14, s9, v242
	v_mfma_f32_32x32x16_bf16 v[64:79], v[172:175], v[92:95], v[64:79]
	v_add_f32_e32 v241, v115, v241
	v_exp_f32_e32 v116, v116
	v_exp_f32_e32 v117, v117
	v_add_f32_e32 v240, v130, v240
	v_fma_f32 v98, v14, s96, v242
	ds_read_b128 v[160:163], v250 offset:18432
	ds_read_b128 v[164:167], v250 offset:18464
	ds_read_b128 v[168:171], v250 offset:18496
	ds_read_b128 v[172:175], v250 offset:18528
	s_waitcnt lgkmcnt(4)
	v_mfma_f32_32x32x16_bf16 v[48:63], v[224:227], v[80:83], v[48:63]
	v_add_f32_e32 v241, v131, v241
	v_exp_f32_e32 v132, v132
	v_exp_f32_e32 v133, v133
	v_add_f32_e32 v240, v116, v240
	v_fma_f32 v99, v14, s97, v242
	s_waitcnt vmcnt(0)
	ds_write_b128 v204, v[148:151] offset:27648
	v_mfma_f32_32x32x16_bf16 v[48:63], v[228:231], v[84:87], v[48:63]
	v_add_f32_e32 v241, v117, v241
	v_exp_f32_e32 v118, v118
	v_exp_f32_e32 v119, v119
	v_add_f32_e32 v240, v132, v240
	v_fma_f32 v100, v14, s94, v242
	ds_write_b128 v200, v[152:155] offset:36864
	v_mfma_f32_32x32x16_bf16 v[48:63], v[232:235], v[88:91], v[48:63]
	v_add_f32_e32 v241, v133, v241
	v_exp_f32_e32 v134, v134
	v_exp_f32_e32 v135, v135
	v_add_f32_e32 v240, v118, v240
	v_fma_f32 v101, v14, s95, v242
	ds_write_b128 v200, v[156:159] offset:46080
	v_mfma_f32_32x32x16_bf16 v[48:63], v[236:239], v[92:95], v[48:63]
	v_add_f32_e32 v241, v119, v241
	v_exp_f32_e32 v120, v120
	v_exp_f32_e32 v121, v121
	v_add_f32_e32 v240, v134, v240
	v_fma_f32 v102, v14, s92, v242
	ds_read_b128 v[224:227], v250 offset:23040
	ds_read_b128 v[228:231], v250 offset:23072
	ds_read_b128 v[232:235], v250 offset:23104
	ds_read_b128 v[236:239], v250 offset:23136
	s_waitcnt lgkmcnt(4)
	v_mfma_f32_32x32x16_bf16 v[32:47], v[160:163], v[80:83], v[32:47]
	v_add_f32_e32 v241, v135, v241
	v_exp_f32_e32 v136, v136
	v_exp_f32_e32 v137, v137
	v_add_f32_e32 v240, v120, v240
	v_fma_f32 v103, v14, s93, v242
	v_mfma_f32_32x32x16_bf16 v[32:47], v[164:167], v[84:87], v[32:47]
	v_add_f32_e32 v241, v121, v241
	v_exp_f32_e32 v122, v122
	v_exp_f32_e32 v123, v123
	v_add_f32_e32 v240, v136, v240
	v_fma_f32 v104, v14, s90, v242
	s_ashr_i32 s35, s34, 31
	s_lshl_b64 s[6:7], s[34:35], 17
	s_lshl_b64 s[10:11], s[34:35], 7
	s_add_u32 s10, s18, s10
	s_addc_u32 s11, s19, s11
	s_add_u32 s6, s6, s100
	s_addc_u32 s7, s7, s101
	global_load_dwordx4 v[148:151], v243, s[6:7]
	v_mfma_f32_32x32x16_bf16 v[32:47], v[168:171], v[88:91], v[32:47]
	v_add_f32_e32 v241, v137, v241
	v_exp_f32_e32 v138, v138
	v_exp_f32_e32 v139, v139
	v_add_f32_e32 v240, v122, v240
	v_fma_f32 v105, v14, s91, v242
	global_load_dwordx4 v[152:155], v0, s[10:11]
	v_mfma_f32_32x32x16_bf16 v[32:47], v[172:175], v[92:95], v[32:47]
	v_add_f32_e32 v241, v123, v241
	v_exp_f32_e32 v124, v124
	v_exp_f32_e32 v125, v125
	v_add_f32_e32 v240, v138, v240
	v_fma_f32 v106, v14, s88, v242
	global_load_dwordx4 v[156:159], v196, s[10:11]
	s_add_i32 s34, s34, -1
	ds_read_b128 v[160:163], v244 offset:4608
	ds_read_b128 v[164:167], v244 offset:4640
	ds_read_b128 v[168:171], v244 offset:4672
	ds_read_b128 v[172:175], v244 offset:4704
	s_waitcnt lgkmcnt(4)
	v_mfma_f32_32x32x16_bf16 v[16:31], v[224:227], v[80:83], v[16:31]
	v_add_f32_e32 v241, v139, v241
	v_exp_f32_e32 v140, v140
	v_exp_f32_e32 v141, v141
	v_add_f32_e32 v240, v124, v240
	v_fma_f32 v107, v14, s89, v242
	v_mfma_f32_32x32x16_bf16 v[16:31], v[228:231], v[84:87], v[16:31]
	v_add_f32_e32 v241, v125, v241
	v_exp_f32_e32 v126, v126
	v_exp_f32_e32 v127, v127
	v_add_f32_e32 v240, v140, v240
	v_fma_f32 v108, v14, s86, v242
	v_mfma_f32_32x32x16_bf16 v[16:31], v[232:235], v[88:91], v[16:31]
	v_add_f32_e32 v241, v141, v241
	v_exp_f32_e32 v142, v142
	v_exp_f32_e32 v143, v143
	v_add_f32_e32 v240, v126, v240
	v_fma_f32 v109, v14, s87, v242
	v_mfma_f32_32x32x16_bf16 v[16:31], v[236:239], v[92:95], v[16:31]
	v_add_f32_e32 v241, v127, v241
	v_fma_f32 v110, v14, s78, v242
	v_fma_f32 v111, v14, s79, v242
	ds_read_b128 v[224:227], v244 offset:0
	ds_read_b128 v[228:231], v244 offset:32
	ds_read_b128 v[232:235], v244 offset:64
	ds_read_b128 v[236:239], v244 offset:96
	s_waitcnt lgkmcnt(4)
	v_mfma_f32_32x32x16_bf16 v[96:111], v[160:163], v[2:5], v[96:111]
	v_mov_b32_e32 v80, v242
	v_add_f32_e32 v81, v14, v242
	v_fma_f32 v82, v14, s62, v242
	v_fma_f32 v83, v14, s63, v242
	v_mfma_f32_32x32x16_bf16 v[96:111], v[164:167], v[6:9], v[96:111]
	v_fma_f32 v84, v14, s64, v242
	v_fma_f32 v85, v14, s65, v242
	v_fma_f32 v86, v14, s66, v242
	v_fma_f32 v87, v14, s67, v242
	v_mfma_f32_32x32x16_bf16 v[96:111], v[168:171], v[10:13], v[96:111]
	v_fma_f32 v88, v14, s68, v242
	v_fma_f32 v89, v14, s69, v242
	v_fma_f32 v90, v14, s70, v242
	v_fma_f32 v91, v14, s71, v242
	v_mfma_f32_32x32x16_bf16 v[96:111], v[172:175], v[144:147], v[96:111]
	v_fma_f32 v92, v14, s72, v242
	v_fma_f32 v93, v14, s73, v242
	v_fma_f32 v94, v14, s76, v242
	v_fma_f32 v95, v14, s77, v242
	ds_read_b128 v[160:163], v250 offset:36864
	ds_read_b128 v[164:167], v250 offset:36896
	ds_read_b128 v[168:171], v250 offset:36928
	ds_read_b128 v[172:175], v250 offset:36960
	s_waitcnt lgkmcnt(4)
	v_mfma_f32_32x32x16_bf16 v[80:95], v[224:227], v[2:5], v[80:95]
	s_nop 0
	v_add_f32_e32 v240, v142, v240
	v_add_f32_e32 v241, v143, v241
	v_cvt_pk_bf16_f32 v112, v112, v113
	v_cvt_pk_bf16_f32 v113, v114, v115
	v_cvt_pk_bf16_f32 v114, v116, v117
	v_mfma_f32_32x32x16_bf16 v[80:95], v[228:231], v[6:9], v[80:95]
	v_cvt_pk_bf16_f32 v115, v118, v119
	v_cvt_pk_bf16_f32 v116, v120, v121
	v_cvt_pk_bf16_f32 v117, v122, v123
	v_cvt_pk_bf16_f32 v118, v124, v125
	v_cvt_pk_bf16_f32 v119, v126, v127
	v_cvt_pk_bf16_f32 v120, v128, v129
	v_mfma_f32_32x32x16_bf16 v[80:95], v[232:235], v[10:13], v[80:95]
	v_cvt_pk_bf16_f32 v121, v130, v131
	v_cvt_pk_bf16_f32 v122, v132, v133
	v_cvt_pk_bf16_f32 v123, v134, v135
	v_cvt_pk_bf16_f32 v124, v136, v137
	v_cvt_pk_bf16_f32 v125, v138, v139
	v_cvt_pk_bf16_f32 v126, v140, v141
	v_mfma_f32_32x32x16_bf16 v[80:95], v[236:239], v[144:147], v[80:95]
	v_cvt_pk_bf16_f32 v127, v142, v143
	v_add_f32_e32 v199, v240, v241
	s_branch .Ld_tail3
